# HGRN scan: all 32 chunk loads of an item in flight at once (one batch) on top of band-step version
# speedup vs baseline: 1.0062x; 1.0062x over previous
.LBB0_596:
	s_or_b64 exec, exec, s[22:23]
	s_barrier
	v_readfirstlane_b32 s3, v0
	s_nop 3
	s_cmp_gt_u32 s3, 0x7f
	s_cbranch_scc1 .LBB0_606
	s_lshr_b32 s24, s20, 4
	s_and_b32 s2, s20, 15
	v_lshrrev_b32_e32 v1, 5, v0
	v_lshl_add_u32 v1, s2, 2, v1
	v_and_b32_e32 v2, 31, v0
	v_lshlrev_b32_e32 v2, 1, v2
	v_lshl_add_u32 v3, v1, 6, v2
	v_lshlrev_b32_e32 v4, 2, v3
	v_lshlrev_b32_e32 v5, 2, v2
	v_lshlrev_b32_e32 v3, 1, v3
	s_lshl_b32 s3, s24, 19
	s_add_u32 s22, s12, s3
	s_addc_u32 s23, s13, 0
	s_lshl_b32 s3, s24, 13
	s_add_u32 s18, s10, s3
	s_addc_u32 s19, s11, 0
	s_lshl_b32 s3, s24, 18
	s_add_u32 s24, s14, s3
	s_addc_u32 s25, s15, 0
	v_mov_b32_e32 v6, 0
	v_mov_b32_e32 v7, 0
	global_load_dwordx2 v[10:11], v4, s[22:23] nt
	global_load_dwordx2 v[80:81], v5, s[18:19] offset:0
	s_add_u32 s22, s22, 0x4000
	s_addc_u32 s23, s23, 0
	global_load_dwordx2 v[12:13], v4, s[22:23] nt
	global_load_dwordx2 v[82:83], v5, s[18:19] offset:256
	s_add_u32 s22, s22, 0x4000
	s_addc_u32 s23, s23, 0
	global_load_dwordx2 v[14:15], v4, s[22:23] nt
	global_load_dwordx2 v[84:85], v5, s[18:19] offset:512
	s_add_u32 s22, s22, 0x4000
	s_addc_u32 s23, s23, 0
	global_load_dwordx2 v[16:17], v4, s[22:23] nt
	global_load_dwordx2 v[86:87], v5, s[18:19] offset:768
	s_add_u32 s22, s22, 0x4000
	s_addc_u32 s23, s23, 0
	global_load_dwordx2 v[18:19], v4, s[22:23] nt
	global_load_dwordx2 v[88:89], v5, s[18:19] offset:1024
	s_add_u32 s22, s22, 0x4000
	s_addc_u32 s23, s23, 0
	global_load_dwordx2 v[20:21], v4, s[22:23] nt
	global_load_dwordx2 v[90:91], v5, s[18:19] offset:1280
	s_add_u32 s22, s22, 0x4000
	s_addc_u32 s23, s23, 0
	global_load_dwordx2 v[22:23], v4, s[22:23] nt
	global_load_dwordx2 v[92:93], v5, s[18:19] offset:1536
	s_add_u32 s22, s22, 0x4000
	s_addc_u32 s23, s23, 0
	global_load_dwordx2 v[24:25], v4, s[22:23] nt
	global_load_dwordx2 v[94:95], v5, s[18:19] offset:1792
	s_add_u32 s22, s22, 0x4000
	s_addc_u32 s23, s23, 0
	global_load_dwordx2 v[26:27], v4, s[22:23] nt
	global_load_dwordx2 v[96:97], v5, s[18:19] offset:2048
	s_add_u32 s22, s22, 0x4000
	s_addc_u32 s23, s23, 0
	global_load_dwordx2 v[28:29], v4, s[22:23] nt
	global_load_dwordx2 v[98:99], v5, s[18:19] offset:2304
	s_add_u32 s22, s22, 0x4000
	s_addc_u32 s23, s23, 0
	global_load_dwordx2 v[30:31], v4, s[22:23] nt
	global_load_dwordx2 v[100:101], v5, s[18:19] offset:2560
	s_add_u32 s22, s22, 0x4000
	s_addc_u32 s23, s23, 0
	global_load_dwordx2 v[32:33], v4, s[22:23] nt
	global_load_dwordx2 v[102:103], v5, s[18:19] offset:2816
	s_add_u32 s22, s22, 0x4000
	s_addc_u32 s23, s23, 0
	global_load_dwordx2 v[34:35], v4, s[22:23] nt
	global_load_dwordx2 v[104:105], v5, s[18:19] offset:3072
	s_add_u32 s22, s22, 0x4000
	s_addc_u32 s23, s23, 0
	global_load_dwordx2 v[36:37], v4, s[22:23] nt
	global_load_dwordx2 v[106:107], v5, s[18:19] offset:3328
	s_add_u32 s22, s22, 0x4000
	s_addc_u32 s23, s23, 0
	global_load_dwordx2 v[38:39], v4, s[22:23] nt
	global_load_dwordx2 v[108:109], v5, s[18:19] offset:3584
	s_add_u32 s22, s22, 0x4000
	s_addc_u32 s23, s23, 0
	global_load_dwordx2 v[40:41], v4, s[22:23] nt
	global_load_dwordx2 v[110:111], v5, s[18:19] offset:3840
	s_add_u32 s22, s22, 0x4000
	s_addc_u32 s23, s23, 0
	s_add_u32 s18, s18, 0x1000
	s_addc_u32 s19, s19, 0
	global_load_dwordx2 v[42:43], v4, s[22:23] nt
	global_load_dwordx2 v[112:113], v5, s[18:19] offset:0
	s_add_u32 s22, s22, 0x4000
	s_addc_u32 s23, s23, 0
	global_load_dwordx2 v[44:45], v4, s[22:23] nt
	global_load_dwordx2 v[114:115], v5, s[18:19] offset:256
	s_add_u32 s22, s22, 0x4000
	s_addc_u32 s23, s23, 0
	global_load_dwordx2 v[46:47], v4, s[22:23] nt
	global_load_dwordx2 v[116:117], v5, s[18:19] offset:512
	s_add_u32 s22, s22, 0x4000
	s_addc_u32 s23, s23, 0
	global_load_dwordx2 v[48:49], v4, s[22:23] nt
	global_load_dwordx2 v[118:119], v5, s[18:19] offset:768
	s_add_u32 s22, s22, 0x4000
	s_addc_u32 s23, s23, 0
	global_load_dwordx2 v[50:51], v4, s[22:23] nt
	global_load_dwordx2 v[120:121], v5, s[18:19] offset:1024
	s_add_u32 s22, s22, 0x4000
	s_addc_u32 s23, s23, 0
	global_load_dwordx2 v[52:53], v4, s[22:23] nt
	global_load_dwordx2 v[122:123], v5, s[18:19] offset:1280
	s_add_u32 s22, s22, 0x4000
	s_addc_u32 s23, s23, 0
	global_load_dwordx2 v[54:55], v4, s[22:23] nt
	global_load_dwordx2 v[124:125], v5, s[18:19] offset:1536
	s_add_u32 s22, s22, 0x4000
	s_addc_u32 s23, s23, 0
	global_load_dwordx2 v[56:57], v4, s[22:23] nt
	global_load_dwordx2 v[126:127], v5, s[18:19] offset:1792
	s_add_u32 s22, s22, 0x4000
	s_addc_u32 s23, s23, 0
	global_load_dwordx2 v[58:59], v4, s[22:23] nt
	global_load_dwordx2 v[128:129], v5, s[18:19] offset:2048
	s_add_u32 s22, s22, 0x4000
	s_addc_u32 s23, s23, 0
	global_load_dwordx2 v[60:61], v4, s[22:23] nt
	global_load_dwordx2 v[130:131], v5, s[18:19] offset:2304
	s_add_u32 s22, s22, 0x4000
	s_addc_u32 s23, s23, 0
	global_load_dwordx2 v[62:63], v4, s[22:23] nt
	global_load_dwordx2 v[132:133], v5, s[18:19] offset:2560
	s_add_u32 s22, s22, 0x4000
	s_addc_u32 s23, s23, 0
	global_load_dwordx2 v[64:65], v4, s[22:23] nt
	global_load_dwordx2 v[134:135], v5, s[18:19] offset:2816
	s_add_u32 s22, s22, 0x4000
	s_addc_u32 s23, s23, 0
	global_load_dwordx2 v[66:67], v4, s[22:23] nt
	global_load_dwordx2 v[136:137], v5, s[18:19] offset:3072
	s_add_u32 s22, s22, 0x4000
	s_addc_u32 s23, s23, 0
	global_load_dwordx2 v[68:69], v4, s[22:23] nt
	global_load_dwordx2 v[138:139], v5, s[18:19] offset:3328
	s_add_u32 s22, s22, 0x4000
	s_addc_u32 s23, s23, 0
	global_load_dwordx2 v[70:71], v4, s[22:23] nt
	global_load_dwordx2 v[140:141], v5, s[18:19] offset:3584
	s_add_u32 s22, s22, 0x4000
	s_addc_u32 s23, s23, 0
	global_load_dwordx2 v[72:73], v4, s[22:23] nt
	global_load_dwordx2 v[142:143], v5, s[18:19] offset:3840
	s_add_u32 s22, s22, 0x4000
	s_addc_u32 s23, s23, 0
	s_add_u32 s18, s18, 0x1000
	s_addc_u32 s19, s19, 0
	v_cvt_pk_bf16_f32 v8, v6, v7
	global_store_dword v3, v8, s[24:25]
	s_add_u32 s24, s24, 0x2000
	s_addc_u32 s25, s25, 0
	s_waitcnt vmcnt(63)
	v_fma_f32 v6, v6, v80, v10
	v_fma_f32 v7, v7, v81, v11
	v_cvt_pk_bf16_f32 v8, v6, v7
	global_store_dword v3, v8, s[24:25]
	s_add_u32 s24, s24, 0x2000
	s_addc_u32 s25, s25, 0
	s_waitcnt vmcnt(62)
	v_fma_f32 v6, v6, v82, v12
	v_fma_f32 v7, v7, v83, v13
	v_cvt_pk_bf16_f32 v8, v6, v7
	global_store_dword v3, v8, s[24:25]
	s_add_u32 s24, s24, 0x2000
	s_addc_u32 s25, s25, 0
	s_waitcnt vmcnt(61)
	v_fma_f32 v6, v6, v84, v14
	v_fma_f32 v7, v7, v85, v15
	v_cvt_pk_bf16_f32 v8, v6, v7
	global_store_dword v3, v8, s[24:25]
	s_add_u32 s24, s24, 0x2000
	s_addc_u32 s25, s25, 0
	s_waitcnt vmcnt(60)
	v_fma_f32 v6, v6, v86, v16
	v_fma_f32 v7, v7, v87, v17
	v_cvt_pk_bf16_f32 v8, v6, v7
	global_store_dword v3, v8, s[24:25]
	s_add_u32 s24, s24, 0x2000
	s_addc_u32 s25, s25, 0
	s_waitcnt vmcnt(59)
	v_fma_f32 v6, v6, v88, v18
	v_fma_f32 v7, v7, v89, v19
	v_cvt_pk_bf16_f32 v8, v6, v7
	global_store_dword v3, v8, s[24:25]
	s_add_u32 s24, s24, 0x2000
	s_addc_u32 s25, s25, 0
	s_waitcnt vmcnt(58)
	v_fma_f32 v6, v6, v90, v20
	v_fma_f32 v7, v7, v91, v21
	v_cvt_pk_bf16_f32 v8, v6, v7
	global_store_dword v3, v8, s[24:25]
	s_add_u32 s24, s24, 0x2000
	s_addc_u32 s25, s25, 0
	s_waitcnt vmcnt(57)
	v_fma_f32 v6, v6, v92, v22
	v_fma_f32 v7, v7, v93, v23
	v_cvt_pk_bf16_f32 v8, v6, v7
	global_store_dword v3, v8, s[24:25]
	s_add_u32 s24, s24, 0x2000
	s_addc_u32 s25, s25, 0
	s_waitcnt vmcnt(56)
	v_fma_f32 v6, v6, v94, v24
	v_fma_f32 v7, v7, v95, v25
	v_cvt_pk_bf16_f32 v8, v6, v7
	global_store_dword v3, v8, s[24:25]
	s_add_u32 s24, s24, 0x2000
	s_addc_u32 s25, s25, 0
	s_waitcnt vmcnt(55)
	v_fma_f32 v6, v6, v96, v26
	v_fma_f32 v7, v7, v97, v27
	v_cvt_pk_bf16_f32 v8, v6, v7
	global_store_dword v3, v8, s[24:25]
	s_add_u32 s24, s24, 0x2000
	s_addc_u32 s25, s25, 0
	s_waitcnt vmcnt(54)
	v_fma_f32 v6, v6, v98, v28
	v_fma_f32 v7, v7, v99, v29
	v_cvt_pk_bf16_f32 v8, v6, v7
	global_store_dword v3, v8, s[24:25]
	s_add_u32 s24, s24, 0x2000
	s_addc_u32 s25, s25, 0
	s_waitcnt vmcnt(53)
	v_fma_f32 v6, v6, v100, v30
	v_fma_f32 v7, v7, v101, v31
	v_cvt_pk_bf16_f32 v8, v6, v7
	global_store_dword v3, v8, s[24:25]
	s_add_u32 s24, s24, 0x2000
	s_addc_u32 s25, s25, 0
	s_waitcnt vmcnt(52)
	v_fma_f32 v6, v6, v102, v32
	v_fma_f32 v7, v7, v103, v33
	v_cvt_pk_bf16_f32 v8, v6, v7
	global_store_dword v3, v8, s[24:25]
	s_add_u32 s24, s24, 0x2000
	s_addc_u32 s25, s25, 0
	s_waitcnt vmcnt(51)
	v_fma_f32 v6, v6, v104, v34
	v_fma_f32 v7, v7, v105, v35
	v_cvt_pk_bf16_f32 v8, v6, v7
	global_store_dword v3, v8, s[24:25]
	s_add_u32 s24, s24, 0x2000
	s_addc_u32 s25, s25, 0
	s_waitcnt vmcnt(50)
	v_fma_f32 v6, v6, v106, v36
	v_fma_f32 v7, v7, v107, v37
	v_cvt_pk_bf16_f32 v8, v6, v7
	global_store_dword v3, v8, s[24:25]
	s_add_u32 s24, s24, 0x2000
	s_addc_u32 s25, s25, 0
	s_waitcnt vmcnt(49)
	v_fma_f32 v6, v6, v108, v38
	v_fma_f32 v7, v7, v109, v39
	v_cvt_pk_bf16_f32 v8, v6, v7
	global_store_dword v3, v8, s[24:25]
	s_add_u32 s24, s24, 0x2000
	s_addc_u32 s25, s25, 0
	s_waitcnt vmcnt(48)
	v_fma_f32 v6, v6, v110, v40
	v_fma_f32 v7, v7, v111, v41
	v_cvt_pk_bf16_f32 v8, v6, v7
	global_store_dword v3, v8, s[24:25]
	s_add_u32 s24, s24, 0x2000
	s_addc_u32 s25, s25, 0
	s_waitcnt vmcnt(47)
	v_fma_f32 v6, v6, v112, v42
	v_fma_f32 v7, v7, v113, v43
	v_cvt_pk_bf16_f32 v8, v6, v7
	global_store_dword v3, v8, s[24:25]
	s_add_u32 s24, s24, 0x2000
	s_addc_u32 s25, s25, 0
	s_waitcnt vmcnt(46)
	v_fma_f32 v6, v6, v114, v44
	v_fma_f32 v7, v7, v115, v45
	v_cvt_pk_bf16_f32 v8, v6, v7
	global_store_dword v3, v8, s[24:25]
	s_add_u32 s24, s24, 0x2000
	s_addc_u32 s25, s25, 0
	s_waitcnt vmcnt(45)
	v_fma_f32 v6, v6, v116, v46
	v_fma_f32 v7, v7, v117, v47
	v_cvt_pk_bf16_f32 v8, v6, v7
	global_store_dword v3, v8, s[24:25]
	s_add_u32 s24, s24, 0x2000
	s_addc_u32 s25, s25, 0
	s_waitcnt vmcnt(44)
	v_fma_f32 v6, v6, v118, v48
	v_fma_f32 v7, v7, v119, v49
	v_cvt_pk_bf16_f32 v8, v6, v7
	global_store_dword v3, v8, s[24:25]
	s_add_u32 s24, s24, 0x2000
	s_addc_u32 s25, s25, 0
	s_waitcnt vmcnt(43)
	v_fma_f32 v6, v6, v120, v50
	v_fma_f32 v7, v7, v121, v51
	v_cvt_pk_bf16_f32 v8, v6, v7
	global_store_dword v3, v8, s[24:25]
	s_add_u32 s24, s24, 0x2000
	s_addc_u32 s25, s25, 0
	s_waitcnt vmcnt(42)
	v_fma_f32 v6, v6, v122, v52
	v_fma_f32 v7, v7, v123, v53
	v_cvt_pk_bf16_f32 v8, v6, v7
	global_store_dword v3, v8, s[24:25]
	s_add_u32 s24, s24, 0x2000
	s_addc_u32 s25, s25, 0
	s_waitcnt vmcnt(41)
	v_fma_f32 v6, v6, v124, v54
	v_fma_f32 v7, v7, v125, v55
	v_cvt_pk_bf16_f32 v8, v6, v7
	global_store_dword v3, v8, s[24:25]
	s_add_u32 s24, s24, 0x2000
	s_addc_u32 s25, s25, 0
	s_waitcnt vmcnt(40)
	v_fma_f32 v6, v6, v126, v56
	v_fma_f32 v7, v7, v127, v57
	v_cvt_pk_bf16_f32 v8, v6, v7
	global_store_dword v3, v8, s[24:25]
	s_add_u32 s24, s24, 0x2000
	s_addc_u32 s25, s25, 0
	s_waitcnt vmcnt(39)
	v_fma_f32 v6, v6, v128, v58
	v_fma_f32 v7, v7, v129, v59
	v_cvt_pk_bf16_f32 v8, v6, v7
	global_store_dword v3, v8, s[24:25]
	s_add_u32 s24, s24, 0x2000
	s_addc_u32 s25, s25, 0
	s_waitcnt vmcnt(38)
	v_fma_f32 v6, v6, v130, v60
	v_fma_f32 v7, v7, v131, v61
	v_cvt_pk_bf16_f32 v8, v6, v7
	global_store_dword v3, v8, s[24:25]
	s_add_u32 s24, s24, 0x2000
	s_addc_u32 s25, s25, 0
	s_waitcnt vmcnt(37)
	v_fma_f32 v6, v6, v132, v62
	v_fma_f32 v7, v7, v133, v63
	v_cvt_pk_bf16_f32 v8, v6, v7
	global_store_dword v3, v8, s[24:25]
	s_add_u32 s24, s24, 0x2000
	s_addc_u32 s25, s25, 0
	s_waitcnt vmcnt(36)
	v_fma_f32 v6, v6, v134, v64
	v_fma_f32 v7, v7, v135, v65
	v_cvt_pk_bf16_f32 v8, v6, v7
	global_store_dword v3, v8, s[24:25]
	s_add_u32 s24, s24, 0x2000
	s_addc_u32 s25, s25, 0
	s_waitcnt vmcnt(35)
	v_fma_f32 v6, v6, v136, v66
	v_fma_f32 v7, v7, v137, v67
	v_cvt_pk_bf16_f32 v8, v6, v7
	global_store_dword v3, v8, s[24:25]
	s_add_u32 s24, s24, 0x2000
	s_addc_u32 s25, s25, 0
	s_waitcnt vmcnt(34)
	v_fma_f32 v6, v6, v138, v68
	v_fma_f32 v7, v7, v139, v69
	v_cvt_pk_bf16_f32 v8, v6, v7
	global_store_dword v3, v8, s[24:25]
	s_add_u32 s24, s24, 0x2000
	s_addc_u32 s25, s25, 0
	s_waitcnt vmcnt(33)
	v_fma_f32 v6, v6, v140, v70
	v_fma_f32 v7, v7, v141, v71
	v_cvt_pk_bf16_f32 v8, v6, v7
	global_store_dword v3, v8, s[24:25]
	s_add_u32 s24, s24, 0x2000
	s_addc_u32 s25, s25, 0
	s_waitcnt vmcnt(32)
	v_fma_f32 v6, v6, v142, v72
	v_fma_f32 v7, v7, v143, v73
	s_branch .LBB0_606
